# attention passes 1 and 2: epilogue stores widened to dwordx4 via permlane16_swap (pass 0 already), P0 rewrite with nt loads
# speedup vs baseline: 1.0227x; 1.0127x over previous
; __device__ __forceinline__ unsigned cvt_pk_bf16(float lo, float hi) { unsigned r; asm volatile("v_cvt_pk_bf16_f32 %0, %1, %2" : "=v"(r) : "v"(lo), "v"(hi)); return r; }
; __device__ __forceinline__ float silu_f(float x) { return x * __builtin_amdgcn_rcpf(1.0f + __builtin_amdgcn_exp2f(-x * LOG2E)); }
;     ...
;         const float rl = 1.0f / l;
;         float Lc = mx + __builtin_amdgcn_logf(l);
;         float wb = rl, wa = 0.f;
;         if (PASS > 0) { const float Lm = fmaxf(Lp, Lc);
;             const float ea = __builtin_amdgcn_exp2f(Lp - Lm), eb = __builtin_amdgcn_exp2f(Lc - Lm), den = ea + eb, rd = 1.0f / den;
;             wa = ea * rd; wb = eb * rd * rl; Lc = Lm + __builtin_amdgcn_logf(den); }
;         if (PASS < 2) { if (fq == 0) LACC[(size_t)qrow * 16 + h] = Lc; }
; #pragma unroll
;         for (int db = 0; db < 8; ++db) { f32x4 v = o[db] * wb;
;             const size_t ocol = (size_t)h * 128 + 16 * db + 4 * fq;
;             if (PASS > 0) { v[0] += wa * bf_lo(pv[db].x); v[1] += wa * bf_hi(pv[db].x); v[2] += wa * bf_lo(pv[db].y); v[3] += wa * bf_hi(pv[db].y); }
;             if (PASS < 2) { u32x2 ov; ov.x = pg8::cvt_pk_bf16(v[0], v[1]); ov.y = pg8::cvt_pk_bf16(v[2], v[3]); *(u32x2*)((char*)OACC + ((unsigned)(h * MT + qrow) * 256u + (unsigned)(32 * db + 8 * fq))) = ov; }
;             else { v[0] *= pg8::silu_f(bf_lo(gv[db].x)); v[1] *= pg8::silu_f(bf_hi(gv[db].x)); v[2] *= pg8::silu_f(bf_lo(gv[db].y)); v[3] *= pg8::silu_f(bf_hi(gv[db].y));
;                 u32x2 ov; ov.x = pg8::cvt_pk_bf16(v[0], v[1]); ov.y = pg8::cvt_pk_bf16(v[2], v[3]); *(u32x2*)((char*)RB + ((unsigned)qrow * (unsigned)(LDB * 2) + (unsigned)(h * 256 + 32 * db + 8 * fq))) = ov; } }
;         asm volatile("s_waitcnt lgkmcnt(0)\n\ts_barrier" ::: "memory");
.LBB0_364:
	s_or_b64 exec, exec, s[0:1]
	v_div_scale_f32 v90, s[0:1], v87, v87, 1.0
	v_rcp_f32_e32 v91, v90
	v_lshl_add_u64 v[88:89], s[92:93], 0, v[186:187]
	s_addk_i32 s33, 0x100
	v_lshl_add_u64 v[190:191], v[190:191], 0, 64
	v_fma_f32 v92, -v90, v91, 1.0
	v_fmac_f32_e32 v91, v92, v91
	v_div_scale_f32 v92, vcc, 1.0, v87, 1.0
	v_mul_f32_e32 v93, v92, v91
	v_fma_f32 v94, -v90, v93, v92
	v_fmac_f32_e32 v93, v94, v91
	v_fma_f32 v90, -v90, v93, v92
	v_div_fmas_f32 v90, v90, v91, v93
	v_div_fixup_f32 v87, v90, v87, 1.0
	v_div_scale_f32 v90, s[0:1], v86, v86, 1.0
	v_rcp_f32_e32 v91, v90
	s_cmpk_lg_i32 s33, 0x400
	v_fma_f32 v92, -v90, v91, 1.0
	v_fmac_f32_e32 v91, v92, v91
	v_div_scale_f32 v92, vcc, 1.0, v86, 1.0
	v_mul_f32_e32 v93, v92, v91
	v_fma_f32 v94, -v90, v93, v92
	v_fmac_f32_e32 v93, v94, v91
	v_fma_f32 v90, -v90, v93, v92
	v_div_fmas_f32 v90, v90, v91, v93
	v_div_fixup_f32 v86, v90, v86, 1.0
	v_mul_f32_e32 v92, v84, v86
	v_mul_f32_e32 v84, v85, v86
	v_mul_f32_e32 v84, v87, v84
	v_and_b32_e32 v86, 16, v168
	v_lshrrev_b32_e32 v87, 1, v86
	v_add_u32_e32 v86, v86, v87
	v_mov_b32_e32 v87, 0
	v_lshl_add_u64 v[90:91], v[88:89], 0, v[86:87]
	s_waitcnt vmcnt(6)
	v_pk_mul_f32 v[100:101], v[84:85], v[100:101] op_sel_hi:[0,1]
	v_pk_mul_f32 v[102:103], v[84:85], v[102:103] op_sel_hi:[0,1]
	v_lshlrev_b32_e32 v93, 16, v142
	v_and_b32_e32 v94, 0xffff0000, v142
	v_fmac_f32_e32 v100, v92, v93
	v_fmac_f32_e32 v101, v92, v94
	v_lshlrev_b32_e32 v93, 16, v143
	v_and_b32_e32 v94, 0xffff0000, v143
	v_fmac_f32_e32 v102, v92, v93
	v_fmac_f32_e32 v103, v92, v94
	v_pk_mul_f32 v[104:105], v[84:85], v[104:105] op_sel_hi:[0,1]
	v_pk_mul_f32 v[106:107], v[84:85], v[106:107] op_sel_hi:[0,1]
	v_lshlrev_b32_e32 v93, 16, v140
	v_and_b32_e32 v94, 0xffff0000, v140
	v_fmac_f32_e32 v104, v92, v93
	v_fmac_f32_e32 v105, v92, v94
	v_lshlrev_b32_e32 v93, 16, v141
	v_and_b32_e32 v94, 0xffff0000, v141
	v_fmac_f32_e32 v106, v92, v93
	v_fmac_f32_e32 v107, v92, v94
	v_cvt_pk_bf16_f32 v100, v100, v101
	v_cvt_pk_bf16_f32 v101, v102, v103
	v_cvt_pk_bf16_f32 v102, v104, v105
	v_cvt_pk_bf16_f32 v103, v106, v107
	s_nop 1
	v_permlane16_swap_b32_e32 v100, v102
	v_permlane16_swap_b32_e32 v101, v103
	global_store_dwordx4 v[90:91], v[100:103], off
	s_waitcnt vmcnt(5)
	v_pk_mul_f32 v[108:109], v[84:85], v[108:109] op_sel_hi:[0,1]
	v_pk_mul_f32 v[110:111], v[84:85], v[110:111] op_sel_hi:[0,1]
	v_lshlrev_b32_e32 v93, 16, v138
	v_and_b32_e32 v94, 0xffff0000, v138
	v_fmac_f32_e32 v108, v92, v93
	v_fmac_f32_e32 v109, v92, v94
	v_lshlrev_b32_e32 v93, 16, v139
	v_and_b32_e32 v94, 0xffff0000, v139
	v_fmac_f32_e32 v110, v92, v93
	v_fmac_f32_e32 v111, v92, v94
	v_pk_mul_f32 v[112:113], v[84:85], v[112:113] op_sel_hi:[0,1]
	v_pk_mul_f32 v[114:115], v[84:85], v[114:115] op_sel_hi:[0,1]
	v_lshlrev_b32_e32 v93, 16, v136
	v_and_b32_e32 v94, 0xffff0000, v136
	v_fmac_f32_e32 v112, v92, v93
	v_fmac_f32_e32 v113, v92, v94
	v_lshlrev_b32_e32 v93, 16, v137
	v_and_b32_e32 v94, 0xffff0000, v137
	v_fmac_f32_e32 v114, v92, v93
	v_fmac_f32_e32 v115, v92, v94
	v_cvt_pk_bf16_f32 v108, v108, v109
	v_cvt_pk_bf16_f32 v109, v110, v111
	v_cvt_pk_bf16_f32 v110, v112, v113
	v_cvt_pk_bf16_f32 v111, v114, v115
	s_nop 1
	v_permlane16_swap_b32_e32 v108, v110
	v_permlane16_swap_b32_e32 v109, v111
	global_store_dwordx4 v[90:91], v[108:111], off offset:64
	s_waitcnt vmcnt(4)
	v_pk_mul_f32 v[116:117], v[84:85], v[116:117] op_sel_hi:[0,1]
	v_pk_mul_f32 v[118:119], v[84:85], v[118:119] op_sel_hi:[0,1]
	v_lshlrev_b32_e32 v93, 16, v134
	v_and_b32_e32 v94, 0xffff0000, v134
	v_fmac_f32_e32 v116, v92, v93
	v_fmac_f32_e32 v117, v92, v94
	v_lshlrev_b32_e32 v93, 16, v135
	v_and_b32_e32 v94, 0xffff0000, v135
	v_fmac_f32_e32 v118, v92, v93
	v_fmac_f32_e32 v119, v92, v94
	v_pk_mul_f32 v[120:121], v[84:85], v[120:121] op_sel_hi:[0,1]
	v_pk_mul_f32 v[122:123], v[84:85], v[122:123] op_sel_hi:[0,1]
	v_lshlrev_b32_e32 v93, 16, v132
	v_and_b32_e32 v94, 0xffff0000, v132
	v_fmac_f32_e32 v120, v92, v93
	v_fmac_f32_e32 v121, v92, v94
	v_lshlrev_b32_e32 v93, 16, v133
	v_and_b32_e32 v94, 0xffff0000, v133
	v_fmac_f32_e32 v122, v92, v93
	v_fmac_f32_e32 v123, v92, v94
	v_cvt_pk_bf16_f32 v116, v116, v117
	v_cvt_pk_bf16_f32 v117, v118, v119
	v_cvt_pk_bf16_f32 v118, v120, v121
	v_cvt_pk_bf16_f32 v119, v122, v123
	s_nop 1
	v_permlane16_swap_b32_e32 v116, v118
	v_permlane16_swap_b32_e32 v117, v119
	global_store_dwordx4 v[90:91], v[116:119], off offset:128
	s_waitcnt vmcnt(3)
	v_pk_mul_f32 v[124:125], v[84:85], v[124:125] op_sel_hi:[0,1]
	v_pk_mul_f32 v[126:127], v[84:85], v[126:127] op_sel_hi:[0,1]
	v_lshlrev_b32_e32 v93, 16, v130
	v_and_b32_e32 v94, 0xffff0000, v130
	v_fmac_f32_e32 v124, v92, v93
	v_fmac_f32_e32 v125, v92, v94
	v_lshlrev_b32_e32 v93, 16, v131
	v_and_b32_e32 v94, 0xffff0000, v131
	v_fmac_f32_e32 v126, v92, v93
	v_fmac_f32_e32 v127, v92, v94
	v_pk_mul_f32 v[80:81], v[84:85], v[80:81] op_sel_hi:[0,1]
	v_pk_mul_f32 v[82:83], v[84:85], v[82:83] op_sel_hi:[0,1]
	v_lshlrev_b32_e32 v93, 16, v128
	v_and_b32_e32 v94, 0xffff0000, v128
	v_fmac_f32_e32 v80, v92, v93
	v_fmac_f32_e32 v81, v92, v94
	v_lshlrev_b32_e32 v93, 16, v129
	v_and_b32_e32 v94, 0xffff0000, v129
	v_fmac_f32_e32 v82, v92, v93
	v_fmac_f32_e32 v83, v92, v94
	v_cvt_pk_bf16_f32 v124, v124, v125
	v_cvt_pk_bf16_f32 v125, v126, v127
	v_cvt_pk_bf16_f32 v126, v80, v81
	v_cvt_pk_bf16_f32 v127, v82, v83
	s_nop 1
	v_permlane16_swap_b32_e32 v124, v126
	v_permlane16_swap_b32_e32 v125, v127
	global_store_dwordx4 v[90:91], v[124:127], off offset:192
	s_waitcnt lgkmcnt(0)
	s_barrier
	v_mov_b64_e32 v[126:127], v[66:67]
	v_mov_b64_e32 v[130:131], v[70:71]
	v_mov_b64_e32 v[134:135], v[74:75]
	v_mov_b64_e32 v[122:123], v[78:79]
	v_mov_b64_e32 v[124:125], v[64:65]
	v_mov_b64_e32 v[128:129], v[68:69]
	v_mov_b64_e32 v[132:133], v[72:73]
	v_mov_b64_e32 v[120:121], v[76:77]
	s_cbranch_scc0 .LBB0_163

; __device__ __forceinline__ unsigned cvt_pk_bf16(float lo, float hi) { unsigned r; asm volatile("v_cvt_pk_bf16_f32 %0, %1, %2" : "=v"(r) : "v"(lo), "v"(hi)); return r; }
;     ...
;         mx = fmaxf(mx, __shfl_xor(mx, 16)); mx = fmaxf(mx, __shfl_xor(mx, 32));
;         float l = 0.f;
; #pragma unroll
;         for (int t = 0; t < 10; ++t)
; #pragma unroll
;             for (int i = 0; i < 4; ++i) { const float p = __builtin_amdgcn_exp2f(s[t][i] - mx); s[t][i] = p; l += p; }
;         l += __shfl_xor(l, 16); l += __shfl_xor(l, 32);
;         bf16x8 pf[5];
; #pragma unroll
;         for (int b = 0; b < 5; ++b) { u32x4 u; u.x = pg8::cvt_pk_bf16(s[2 * b][0], s[2 * b][1]); u.y = pg8::cvt_pk_bf16(s[2 * b][2], s[2 * b][3]);
;             u.z = pg8::cvt_pk_bf16(s[2 * b + 1][0], s[2 * b + 1][1]); u.w = pg8::cvt_pk_bf16(s[2 * b + 1][2], s[2 * b + 1][3]); pf[b] = __builtin_bit_cast(bf16x8, u); }
;         float Lp = 0.f; u32x2 pv[8]; u32x2 gv[8];
;         if (PASS > 0) { Lp = LACC[(size_t)qrow * 16 + h];
; #pragma unroll
;             for (int db = 0; db < 8; ++db) pv[db] = *(const u32x2*)((const char*)OACC + ((unsigned)(h * MT + qrow) * 256u + (unsigned)(32 * db + 8 * fq))); }
;         if (PASS == 2) {
; #pragma unroll
;             for (int db = 0; db < 8; ++db) gv[db] = *(const u32x2*)((const char*)RB + ((unsigned)qrow * (unsigned)(LDB * 2) + (unsigned)(h * 256 + 32 * db + 8 * fq))); }
.LBB0_532:
	v_and_b32_e32 v81, 64, v205
	v_xor_b32_e32 v80, 16, v205
	v_add_u32_e32 v81, 64, v81
	v_cmp_lt_i32_e32 vcc, v80, v81
	s_waitcnt lgkmcnt(2)
	v_max_f32_e32 v82, v160, v160
	v_readlane_b32 s35, v255, 20
	v_cndmask_b32_e32 v80, v205, v80, vcc
	v_lshlrev_b32_e32 v88, 2, v80
	ds_bpermute_b32 v80, v88, v160
	s_and_b32 s34, s35, 0xfffff800
	s_and_b64 s[0:1], s[18:19], exec
	s_cselect_b32 s0, s34, 0x2000
	s_add_i32 s2, s2, s0
	s_waitcnt lgkmcnt(0)
	v_max_f32_e32 v80, v80, v80
	v_max_f32_e32 v80, v82, v80
	v_xor_b32_e32 v82, 32, v205
	v_cmp_lt_i32_e32 vcc, v82, v81
	s_mul_i32 s0, s31, 0x6000
	v_readlane_b32 s18, v255, 44
	v_cndmask_b32_e32 v81, v205, v82, vcc
	v_lshlrev_b32_e32 v89, 2, v81
	ds_bpermute_b32 v81, v89, v80
	v_add_u32_e32 v82, s33, v187
	v_lshl_add_u32 v84, v82, 4, s2
	v_ashrrev_i32_e32 v85, 31, v84
	v_lshlrev_b64 v[86:87], 6, v[84:85]
	s_waitcnt lgkmcnt(0)
	v_max_f32_e32 v81, v81, v81
	v_max_f32_e32 v166, v80, v81
	v_sub_f32_e32 v80, v120, v166
	v_exp_f32_e32 v90, v80
	v_sub_f32_e32 v80, v121, v166
	v_exp_f32_e32 v91, v80
	v_sub_f32_e32 v80, v122, v166
	v_exp_f32_e32 v92, v80
	v_sub_f32_e32 v80, v123, v166
	v_exp_f32_e32 v93, v80
	v_sub_f32_e32 v80, v124, v166
	v_exp_f32_e32 v94, v80
	v_sub_f32_e32 v80, v125, v166
	v_exp_f32_e32 v95, v80
	v_sub_f32_e32 v80, v126, v166
	v_exp_f32_e32 v96, v80
	v_sub_f32_e32 v80, v127, v166
	v_exp_f32_e32 v97, v80
	v_sub_f32_e32 v80, v128, v166
	v_exp_f32_e32 v98, v80
	v_sub_f32_e32 v80, v129, v166
	v_exp_f32_e32 v99, v80
	v_sub_f32_e32 v80, v130, v166
	v_exp_f32_e32 v116, v80
	v_sub_f32_e32 v80, v131, v166
	v_exp_f32_e32 v117, v80
	v_sub_f32_e32 v80, v132, v166
	v_exp_f32_e32 v118, v80
	v_sub_f32_e32 v80, v133, v166
	v_exp_f32_e32 v119, v80
	v_sub_f32_e32 v80, v134, v166
	v_exp_f32_e32 v120, v80
	v_sub_f32_e32 v80, v135, v166
	v_exp_f32_e32 v121, v80
	v_sub_f32_e32 v80, v136, v166
	v_exp_f32_e32 v122, v80
	v_sub_f32_e32 v80, v137, v166
	v_exp_f32_e32 v123, v80
	v_sub_f32_e32 v80, v138, v166
	v_exp_f32_e32 v124, v80
	v_sub_f32_e32 v80, v139, v166
	v_exp_f32_e32 v125, v80
	v_sub_f32_e32 v80, v140, v166
	v_exp_f32_e32 v126, v80
	v_sub_f32_e32 v80, v141, v166
	v_exp_f32_e32 v127, v80
	v_sub_f32_e32 v80, v142, v166
	v_exp_f32_e32 v206, v80
	v_sub_f32_e32 v80, v143, v166
	v_exp_f32_e32 v207, v80
	v_sub_f32_e32 v80, v144, v166
	v_exp_f32_e32 v208, v80
	v_sub_f32_e32 v80, v145, v166
	v_exp_f32_e32 v209, v80
	v_sub_f32_e32 v80, v146, v166
	v_exp_f32_e32 v210, v80
	v_sub_f32_e32 v80, v147, v166
	v_exp_f32_e32 v211, v80
	v_sub_f32_e32 v80, v148, v166
	v_exp_f32_e32 v212, v80
	v_sub_f32_e32 v80, v149, v166
	v_exp_f32_e32 v213, v80
	v_sub_f32_e32 v80, v150, v166
	v_exp_f32_e32 v214, v80
	v_sub_f32_e32 v80, v151, v166
	v_exp_f32_e32 v215, v80
	v_sub_f32_e32 v80, v152, v166
	v_exp_f32_e32 v216, v80
	v_sub_f32_e32 v80, v153, v166
	v_exp_f32_e32 v217, v80
	v_sub_f32_e32 v80, v156, v166
	v_exp_f32_e32 v218, v80
	v_sub_f32_e32 v80, v157, v166
	v_exp_f32_e32 v219, v80
	v_sub_f32_e32 v80, v154, v166
	v_exp_f32_e32 v220, v80
	v_sub_f32_e32 v80, v155, v166
	v_exp_f32_e32 v221, v80
	v_sub_f32_e32 v80, v158, v166
	v_lshl_add_u64 v[86:87], s[80:81], 0, v[86:87]
	s_lshl_b32 s2, s31, 2
	v_add_u32_e32 v85, s0, v84
	v_exp_f32_e32 v222, v80
	v_sub_f32_e32 v80, v159, v166
	v_lshl_add_u64 v[86:87], v[86:87], 0, s[2:3]
	v_lshl_or_b32 v85, v85, 8, v201
	v_exp_f32_e32 v223, v80
	v_cvt_pk_bf16_f32 v80, v90, v91
	v_cvt_pk_bf16_f32 v81, v92, v93
	v_cvt_pk_bf16_f32 v82, v94, v95
	v_cvt_pk_bf16_f32 v83, v96, v97
	v_cvt_pk_bf16_f32 v100, v98, v99
	v_cvt_pk_bf16_f32 v101, v116, v117
	v_cvt_pk_bf16_f32 v102, v118, v119
	v_cvt_pk_bf16_f32 v103, v120, v121
	v_cvt_pk_bf16_f32 v104, v122, v123
	v_cvt_pk_bf16_f32 v105, v124, v125
	v_cvt_pk_bf16_f32 v106, v126, v127
	v_cvt_pk_bf16_f32 v107, v206, v207
	v_cvt_pk_bf16_f32 v108, v208, v209
	v_cvt_pk_bf16_f32 v109, v210, v211
	v_cvt_pk_bf16_f32 v110, v212, v213
	v_cvt_pk_bf16_f32 v111, v214, v215
	v_cvt_pk_bf16_f32 v112, v216, v217
	v_cvt_pk_bf16_f32 v113, v218, v219
	v_cvt_pk_bf16_f32 v114, v220, v221
	v_cvt_pk_bf16_f32 v115, v222, v223
	global_load_dword v242, v[86:87], off
	global_load_dwordx2 v[156:157], v85, s[92:93]
	global_load_dwordx2 v[152:153], v85, s[92:93] offset:32
	global_load_dwordx2 v[148:149], v85, s[92:93] offset:64
	global_load_dwordx2 v[144:145], v85, s[92:93] offset:96
	global_load_dwordx2 v[140:141], v85, s[92:93] offset:128
	global_load_dwordx2 v[136:137], v85, s[92:93] offset:160
	global_load_dwordx2 v[132:133], v85, s[92:93] offset:192
	global_load_dwordx2 v[128:129], v85, s[92:93] offset:224
	v_lshlrev_b32_e32 v84, 13, v84
	s_lshl_b32 s0, s31, 8
	v_or3_b32 v182, v84, s0, v201
	v_readlane_b32 s19, v255, 45
	v_or_b32_e32 v163, 0x80, v182
	v_or_b32_e32 v167, 32, v182
	v_or_b32_e32 v165, 64, v182
	v_or_b32_e32 v164, 0x60, v182
	s_nop 0
	global_load_dwordx2 v[158:159], v182, s[18:19]
	global_load_dwordx2 v[154:155], v167, s[18:19]
	global_load_dwordx2 v[150:151], v165, s[18:19]
	global_load_dwordx2 v[146:147], v164, s[18:19]
	v_or_b32_e32 v162, 0xa0, v182
	v_or_b32_e32 v161, 0xc0, v182
	v_or_b32_e32 v160, 0xe0, v182
	global_load_dwordx2 v[142:143], v163, s[18:19]
	global_load_dwordx2 v[138:139], v162, s[18:19]
	global_load_dwordx2 v[134:135], v161, s[18:19]
	global_load_dwordx2 v[130:131], v160, s[18:19]
	v_add_f32_e32 v84, 0, v90
	v_add_f32_e32 v84, v91, v84
	v_add_f32_e32 v84, v92, v84
	v_add_f32_e32 v84, v93, v84
	v_add_f32_e32 v84, v94, v84
	v_add_f32_e32 v84, v95, v84
	v_add_f32_e32 v84, v96, v84
	v_add_f32_e32 v84, v97, v84
	v_add_f32_e32 v84, v98, v84
	v_add_f32_e32 v84, v99, v84
	v_add_f32_e32 v84, v116, v84
	v_add_f32_e32 v84, v117, v84
	v_add_f32_e32 v84, v118, v84
	v_add_f32_e32 v84, v119, v84
	v_add_f32_e32 v84, v120, v84
	v_add_f32_e32 v84, v121, v84
	v_add_f32_e32 v84, v122, v84
	v_add_f32_e32 v84, v123, v84
	v_add_f32_e32 v84, v124, v84
	v_add_f32_e32 v84, v125, v84
	v_add_f32_e32 v84, v126, v84
	v_add_f32_e32 v84, v127, v84
	v_add_f32_e32 v84, v206, v84
	v_add_f32_e32 v84, v207, v84
	v_add_f32_e32 v84, v208, v84
	v_add_f32_e32 v84, v209, v84
	v_add_f32_e32 v84, v210, v84
	v_add_f32_e32 v84, v211, v84
	v_add_f32_e32 v84, v212, v84
	v_add_f32_e32 v84, v213, v84
	v_add_f32_e32 v84, v214, v84
	v_add_f32_e32 v84, v215, v84
	v_add_f32_e32 v84, v216, v84
	v_add_f32_e32 v84, v217, v84
	v_add_f32_e32 v84, v218, v84
	v_add_f32_e32 v84, v219, v84
	v_add_f32_e32 v84, v220, v84
	v_add_f32_e32 v84, v221, v84
	v_add_f32_e32 v84, v222, v84
	v_add_f32_e32 v84, v223, v84
	ds_bpermute_b32 v85, v88, v84
	s_waitcnt lgkmcnt(0)
; #define LAS __attribute__((address_space(3)))
; #define ATT_LDV(BUF, DB) _Pragma("unroll") for (int b = 0; b < 5; ++b) { vl[BUF][b] = vtr(vbase + (32 * b) * VPITCH + (DB) * 32); vh[BUF][b] = vtr(vbase + (32 * b + 16) * VPITCH + (DB) * 32); }
;     ...
;         l += __shfl_xor(l, 16); l += __shfl_xor(l, 32);
;     ...
;         f32x4 o[8];
;         const int q4 = (lane & 15) >> 2, p4 = lane & 3;
;         LAS const unsigned char* vbase = lds + VOFF + (16 * ts + 4 * fq + q4) * VPITCH + p4 * 8;
;         {
;             s16x4 vl[2][5], vh[2][5];
;     ...
;             ATT_LDV(0, 0)
; #pragma unroll
;             for (int db = 0; db < 8; ++db) {
;                 if (db + 1 < 8) { ATT_LDV((db + 1) & 1, db + 1) }
;                 __builtin_amdgcn_sched_barrier(0);
;                 o[db] = (f32x4){0.f, 0.f, 0.f, 0.f};
; #pragma unroll
;                 for (int b = 0; b < 5; ++b) { const s16x4 lo = vl[db & 1][b], hi = vh[db & 1][b];
;                     const bf16x8 vf = (bf16x8){lo[0], lo[1], lo[2], lo[3], hi[0], hi[1], hi[2], hi[3]};
;                     o[db] = __builtin_amdgcn_mfma_f32_16x16x32_bf16(vf, pf[b], o[db], 0, 0, 0); }
;                 __builtin_amdgcn_sched_barrier(0);
;             }
;     ...
;         }
	v_add_f32_e32 v243, v84, v85
	ds_bpermute_b32 v244, v89, v243
	ds_read_b64_tr_b16 v[86:87], v202 offset:4608
	ds_read_b64_tr_b16 v[84:85], v202
	ds_read_b64_tr_b16 v[90:91], v202 offset:4640
	ds_read_b64_tr_b16 v[88:89], v202 offset:32
	ds_read_b64_tr_b16 v[92:93], v202 offset:9216
	ds_read_b64_tr_b16 v[94:95], v202 offset:13824
	ds_read_b64_tr_b16 v[98:99], v202 offset:13856
	ds_read_b64_tr_b16 v[96:97], v202 offset:9248
	ds_read_b64_tr_b16 v[116:117], v202 offset:18432
	ds_read_b64_tr_b16 v[118:119], v202 offset:23040
	ds_read_b64_tr_b16 v[122:123], v202 offset:23072
	ds_read_b64_tr_b16 v[120:121], v202 offset:18464
	ds_read_b64_tr_b16 v[124:125], v202 offset:27648
	ds_read_b64_tr_b16 v[126:127], v202 offset:32256
	ds_read_b64_tr_b16 v[208:209], v202 offset:32288
	ds_read_b64_tr_b16 v[206:207], v202 offset:27680
	ds_read_b64_tr_b16 v[210:211], v202 offset:36864
	ds_read_b64_tr_b16 v[212:213], v202 offset:41472
	ds_read_b64_tr_b16 v[216:217], v202 offset:41504
	ds_read_b64_tr_b16 v[214:215], v202 offset:36896
	s_waitcnt lgkmcnt(14)
	v_mfma_f32_16x16x32_bf16 v[84:87], v[84:87], v[80:83], 0
	v_mfma_f32_16x16x32_bf16 v[84:87], v[92:95], v[100:103], v[84:87]
	s_waitcnt lgkmcnt(10)
	v_mfma_f32_16x16x32_bf16 v[84:87], v[116:119], v[104:107], v[84:87]
	s_waitcnt lgkmcnt(6)
	v_mfma_f32_16x16x32_bf16 v[84:87], v[124:127], v[108:111], v[84:87]
	s_waitcnt lgkmcnt(2)
	v_mfma_f32_16x16x32_bf16 v[124:127], v[210:213], v[112:115], v[84:87]
	s_nop 5
	ds_read_b64_tr_b16 v[84:85], v202 offset:9280
	ds_read_b64_tr_b16 v[86:87], v202 offset:13888
	ds_read_b64_tr_b16 v[92:93], v202 offset:18496
	ds_read_b64_tr_b16 v[94:95], v202 offset:23104
	ds_read_b64_tr_b16 v[116:117], v202 offset:27712
	ds_read_b64_tr_b16 v[118:119], v202 offset:32320
	ds_read_b64_tr_b16 v[210:211], v202 offset:64
	ds_read_b64_tr_b16 v[212:213], v202 offset:4672
	ds_read_b64_tr_b16 v[218:219], v202 offset:36928
	ds_read_b64_tr_b16 v[220:221], v202 offset:41536
	v_mfma_f32_16x16x32_bf16 v[88:91], v[88:91], v[80:83], 0
	v_mfma_f32_16x16x32_bf16 v[88:91], v[96:99], v[100:103], v[88:91]
	v_mfma_f32_16x16x32_bf16 v[88:91], v[120:123], v[104:107], v[88:91]
	v_mfma_f32_16x16x32_bf16 v[88:91], v[206:209], v[108:111], v[88:91]
	s_waitcnt lgkmcnt(10)
	v_mfma_f32_16x16x32_bf16 v[120:123], v[214:217], v[112:115], v[88:91]
	s_nop 5
	ds_read_b64_tr_b16 v[88:89], v202 offset:9312
	ds_read_b64_tr_b16 v[90:91], v202 offset:13920
	ds_read_b64_tr_b16 v[96:97], v202 offset:18528
	ds_read_b64_tr_b16 v[98:99], v202 offset:23136
	ds_read_b64_tr_b16 v[206:207], v202 offset:27744
	ds_read_b64_tr_b16 v[208:209], v202 offset:32352
	ds_read_b64_tr_b16 v[214:215], v202 offset:96
	ds_read_b64_tr_b16 v[216:217], v202 offset:4704
	ds_read_b64_tr_b16 v[222:223], v202 offset:36960
	ds_read_b64_tr_b16 v[224:225], v202 offset:41568
	s_waitcnt lgkmcnt(12)
	v_mfma_f32_16x16x32_bf16 v[210:213], v[210:213], v[80:83], 0
	v_mfma_f32_16x16x32_bf16 v[84:87], v[84:87], v[100:103], v[210:213]
	v_mfma_f32_16x16x32_bf16 v[84:87], v[92:95], v[104:107], v[84:87]
	v_mfma_f32_16x16x32_bf16 v[84:87], v[116:119], v[108:111], v[84:87]
	s_waitcnt lgkmcnt(10)
	v_mfma_f32_16x16x32_bf16 v[116:119], v[218:221], v[112:115], v[84:87]
	s_nop 5
	ds_read_b64_tr_b16 v[84:85], v202 offset:9344
	ds_read_b64_tr_b16 v[86:87], v202 offset:13952
	ds_read_b64_tr_b16 v[92:93], v202 offset:18560
	ds_read_b64_tr_b16 v[94:95], v202 offset:23168
	ds_read_b64_tr_b16 v[210:211], v202 offset:27776
	ds_read_b64_tr_b16 v[212:213], v202 offset:32384
	ds_read_b64_tr_b16 v[218:219], v202 offset:128
	ds_read_b64_tr_b16 v[220:221], v202 offset:4736
	ds_read_b64_tr_b16 v[226:227], v202 offset:36992
	ds_read_b64_tr_b16 v[228:229], v202 offset:41600
	s_waitcnt lgkmcnt(12)
	v_mfma_f32_16x16x32_bf16 v[214:217], v[214:217], v[80:83], 0
	v_mfma_f32_16x16x32_bf16 v[88:91], v[88:91], v[100:103], v[214:217]
	v_mfma_f32_16x16x32_bf16 v[88:91], v[96:99], v[104:107], v[88:91]
	v_mfma_f32_16x16x32_bf16 v[88:91], v[206:209], v[108:111], v[88:91]
	s_waitcnt lgkmcnt(10)
	v_mfma_f32_16x16x32_bf16 v[96:99], v[222:225], v[112:115], v[88:91]
	s_nop 5
	ds_read_b64_tr_b16 v[88:89], v202 offset:9376
	ds_read_b64_tr_b16 v[90:91], v202 offset:13984
	ds_read_b64_tr_b16 v[206:207], v202 offset:18592
	ds_read_b64_tr_b16 v[208:209], v202 offset:23200
	ds_read_b64_tr_b16 v[214:215], v202 offset:27808
	ds_read_b64_tr_b16 v[216:217], v202 offset:32416
	ds_read_b64_tr_b16 v[222:223], v202 offset:160
	ds_read_b64_tr_b16 v[224:225], v202 offset:4768
	ds_read_b64_tr_b16 v[230:231], v202 offset:37024
	ds_read_b64_tr_b16 v[232:233], v202 offset:41632
	s_waitcnt lgkmcnt(12)
	v_mfma_f32_16x16x32_bf16 v[218:221], v[218:221], v[80:83], 0
	v_mfma_f32_16x16x32_bf16 v[84:87], v[84:87], v[100:103], v[218:221]
	v_mfma_f32_16x16x32_bf16 v[84:87], v[92:95], v[104:107], v[84:87]
	v_mfma_f32_16x16x32_bf16 v[84:87], v[210:213], v[108:111], v[84:87]
	s_waitcnt lgkmcnt(10)
	v_mfma_f32_16x16x32_bf16 v[92:95], v[226:229], v[112:115], v[84:87]
	s_nop 5
	ds_read_b64_tr_b16 v[84:85], v202 offset:9408
	ds_read_b64_tr_b16 v[86:87], v202 offset:14016
	ds_read_b64_tr_b16 v[210:211], v202 offset:18624
	ds_read_b64_tr_b16 v[212:213], v202 offset:23232
	ds_read_b64_tr_b16 v[218:219], v202 offset:27840
	ds_read_b64_tr_b16 v[220:221], v202 offset:32448
	ds_read_b64_tr_b16 v[226:227], v202 offset:192
	ds_read_b64_tr_b16 v[228:229], v202 offset:4800
	ds_read_b64_tr_b16 v[234:235], v202 offset:37056
	ds_read_b64_tr_b16 v[236:237], v202 offset:41664
	s_waitcnt lgkmcnt(12)
	v_mfma_f32_16x16x32_bf16 v[222:225], v[222:225], v[80:83], 0
	v_mfma_f32_16x16x32_bf16 v[88:91], v[88:91], v[100:103], v[222:225]
	v_mfma_f32_16x16x32_bf16 v[88:91], v[206:209], v[104:107], v[88:91]
	v_mfma_f32_16x16x32_bf16 v[88:91], v[214:217], v[108:111], v[88:91]
	s_waitcnt lgkmcnt(10)
; __device__ __forceinline__ unsigned cvt_pk_bf16(float lo, float hi) { unsigned r; asm volatile("v_cvt_pk_bf16_f32 %0, %1, %2" : "=v"(r) : "v"(lo), "v"(hi)); return r; }
; __device__ __forceinline__ float silu_f(float x) { return x * __builtin_amdgcn_rcpf(1.0f + __builtin_amdgcn_exp2f(-x * LOG2E)); }
;     ...
;         const float rl = 1.0f / l;
;         float Lc = mx + __builtin_amdgcn_logf(l);
;         float wb = rl, wa = 0.f;
;         if (PASS > 0) { const float Lm = fmaxf(Lp, Lc);
;             const float ea = __builtin_amdgcn_exp2f(Lp - Lm), eb = __builtin_amdgcn_exp2f(Lc - Lm), den = ea + eb, rd = 1.0f / den;
;             wa = ea * rd; wb = eb * rd * rl; Lc = Lm + __builtin_amdgcn_logf(den); }
;         if (PASS < 2) { if (fq == 0) LACC[(size_t)qrow * 16 + h] = Lc; }
; #pragma unroll
;         for (int db = 0; db < 8; ++db) { f32x4 v = o[db] * wb;
;             const size_t ocol = (size_t)h * 128 + 16 * db + 4 * fq;
;             if (PASS > 0) { v[0] += wa * bf_lo(pv[db].x); v[1] += wa * bf_hi(pv[db].x); v[2] += wa * bf_lo(pv[db].y); v[3] += wa * bf_hi(pv[db].y); }
;             if (PASS < 2) { u32x2 ov; ov.x = pg8::cvt_pk_bf16(v[0], v[1]); ov.y = pg8::cvt_pk_bf16(v[2], v[3]); *(u32x2*)((char*)OACC + ((unsigned)(h * MT + qrow) * 256u + (unsigned)(32 * db + 8 * fq))) = ov; }
;             else { v[0] *= pg8::silu_f(bf_lo(gv[db].x)); v[1] *= pg8::silu_f(bf_hi(gv[db].x)); v[2] *= pg8::silu_f(bf_lo(gv[db].y)); v[3] *= pg8::silu_f(bf_hi(gv[db].y));
;                 u32x2 ov; ov.x = pg8::cvt_pk_bf16(v[0], v[1]); ov.y = pg8::cvt_pk_bf16(v[2], v[3]); *(u32x2*)((char*)RB + ((unsigned)qrow * (unsigned)(LDB * 2) + (unsigned)(h * 256 + 32 * db + 8 * fq))) = ov; } }
	v_mfma_f32_16x16x32_bf16 v[88:91], v[230:233], v[112:115], v[88:91]
	ds_read_b64_tr_b16 v[206:207], v202 offset:9440
	ds_read_b64_tr_b16 v[208:209], v202 offset:14048
	ds_read_b64_tr_b16 v[214:215], v202 offset:18656
	ds_read_b64_tr_b16 v[216:217], v202 offset:23264
	ds_read_b64_tr_b16 v[222:223], v202 offset:27872
	ds_read_b64_tr_b16 v[224:225], v202 offset:32480
	ds_read_b64_tr_b16 v[230:231], v202 offset:224
	ds_read_b64_tr_b16 v[232:233], v202 offset:4832
	ds_read_b64_tr_b16 v[238:239], v202 offset:37088
	ds_read_b64_tr_b16 v[240:241], v202 offset:41696
	s_waitcnt lgkmcnt(12)
	v_mfma_f32_16x16x32_bf16 v[226:229], v[226:229], v[80:83], 0
	v_mfma_f32_16x16x32_bf16 v[84:87], v[84:87], v[100:103], v[226:229]
	v_mfma_f32_16x16x32_bf16 v[84:87], v[210:213], v[104:107], v[84:87]
	v_mfma_f32_16x16x32_bf16 v[84:87], v[218:221], v[108:111], v[84:87]
	s_waitcnt lgkmcnt(10)
	v_mfma_f32_16x16x32_bf16 v[84:87], v[234:237], v[112:115], v[84:87]
	s_waitcnt lgkmcnt(2)
	v_mfma_f32_16x16x32_bf16 v[80:83], v[230:233], v[80:83], 0
	v_mfma_f32_16x16x32_bf16 v[80:83], v[206:209], v[100:103], v[80:83]
	v_mfma_f32_16x16x32_bf16 v[80:83], v[214:217], v[104:107], v[80:83]
	v_mfma_f32_16x16x32_bf16 v[80:83], v[222:225], v[108:111], v[80:83]
	s_waitcnt lgkmcnt(0)
	v_mfma_f32_16x16x32_bf16 v[80:83], v[238:241], v[112:115], v[80:83]
	v_add_f32_e32 v100, v243, v244
	v_log_f32_e32 v103, v100
	v_div_scale_f32 v101, s[0:1], v100, v100, 1.0
	v_rcp_f32_e32 v102, v101
	v_add_f32_e32 v103, v166, v103
	s_waitcnt vmcnt(16)
	v_max_f32_e32 v106, v242, v242
	v_max_f32_e32 v106, v106, v103
	v_fma_f32 v104, -v101, v102, 1.0
	v_sub_f32_e32 v107, v242, v106
	v_sub_f32_e32 v103, v103, v106
	v_fmac_f32_e32 v102, v104, v102
	v_div_scale_f32 v104, vcc, 1.0, v100, 1.0
	v_exp_f32_e32 v107, v107
	v_exp_f32_e32 v103, v103
	v_mul_f32_e32 v105, v104, v102
	v_fma_f32 v106, -v101, v105, v104
	v_fmac_f32_e32 v105, v106, v102
	v_fma_f32 v101, -v101, v105, v104
	v_add_f32_e32 v104, v107, v103
	v_div_scale_f32 v106, s[0:1], v104, v104, 1.0
	v_rcp_f32_e32 v108, v106
	v_div_fmas_f32 v101, v101, v102, v105
	v_div_fixup_f32 v100, v101, v100, 1.0
	s_waitcnt vmcnt(7)
	v_and_b32_e32 v110, 0xffff0000, v158
	v_fma_f32 v101, -v106, v108, 1.0
	v_fmac_f32_e32 v108, v101, v108
	v_div_scale_f32 v101, vcc, 1.0, v104, 1.0
	v_mul_f32_e32 v102, v101, v108
	v_fma_f32 v105, -v106, v102, v101
	v_fmac_f32_e32 v102, v105, v108
	v_fma_f32 v101, -v106, v102, v101
	v_div_fmas_f32 v101, v101, v108, v102
	v_div_fixup_f32 v102, v101, v104, 1.0
	v_mul_f32_e32 v101, v107, v102
	v_mul_f32_e32 v102, v103, v102
	v_lshlrev_b32_e32 v104, 16, v158
	v_mul_f32_e32 v102, v100, v102
	v_mul_f32_e32 v100, 0xbfb8aa3b, v104
	v_exp_f32_e32 v100, v100
	v_pk_mul_f32 v[106:107], v[102:103], v[126:127] op_sel_hi:[0,1]
	v_pk_mul_f32 v[108:109], v[102:103], v[124:125] op_sel_hi:[0,1]
	v_mul_f32_e32 v103, 0xbfb8aa3b, v110
	v_add_f32_e32 v100, 1.0, v100
	v_rcp_f32_e32 v100, v100
	v_lshlrev_b32_e32 v105, 16, v156
	v_exp_f32_e32 v103, v103
	v_and_b32_e32 v111, 0xffff0000, v156
	v_pk_mul_f32 v[104:105], v[100:101], v[104:105]
	v_readlane_b32 s0, v255, 21
	v_add_f32_e32 v100, v105, v108
	v_mul_f32_e32 v112, v104, v100
	v_lshlrev_b32_e32 v104, 16, v159
	v_add_f32_e32 v100, 1.0, v103
	v_mul_f32_e32 v103, 0xbfb8aa3b, v104
	v_rcp_f32_e32 v100, v100
	v_exp_f32_e32 v103, v103
	v_and_b32_e32 v108, 0xffff0000, v159
	s_add_i32 s35, s35, s0
	v_pk_mul_f32 v[110:111], v[100:101], v[110:111]
	v_add_f32_e32 v100, 1.0, v103
	v_mul_f32_e32 v103, 0xbfb8aa3b, v108
	v_rcp_f32_e32 v100, v100
	v_exp_f32_e32 v103, v103
	v_add_f32_e32 v105, v111, v109
	v_mul_f32_e32 v110, v110, v105
	v_lshlrev_b32_e32 v105, 16, v157
	v_pk_mul_f32 v[104:105], v[100:101], v[104:105]
	v_add_f32_e32 v100, 1.0, v103
	v_rcp_f32_e32 v100, v100
	v_add_f32_e32 v103, v105, v106
	v_and_b32_e32 v109, 0xffff0000, v157
	v_mul_f32_e32 v103, v104, v103
	v_pk_mul_f32 v[104:105], v[100:101], v[108:109]
	v_pk_mul_f32 v[108:109], v[102:103], v[120:121] op_sel_hi:[0,1]
	v_add_f32_e32 v100, v105, v107
	v_mul_f32_e32 v100, v104, v100
	v_cvt_pk_bf16_f32 v104, v112, v110
	v_cvt_pk_bf16_f32 v105, v103, v100
	v_mov_b32_e32 v208, v104
	v_mov_b32_e32 v209, v105
	v_and_b32_e32 v224, 16, v168
	v_lshrrev_b32_e32 v225, 1, v224
	v_add_u32_e32 v224, v224, v225
	s_waitcnt vmcnt(6)
	v_lshlrev_b32_e32 v104, 16, v154
	v_mul_f32_e32 v100, 0xbfb8aa3b, v104
	v_exp_f32_e32 v100, v100
	v_and_b32_e32 v110, 0xffff0000, v154
	v_pk_mul_f32 v[106:107], v[102:103], v[122:123] op_sel_hi:[0,1]
	v_mul_f32_e32 v103, 0xbfb8aa3b, v110
	v_add_f32_e32 v100, 1.0, v100
	v_rcp_f32_e32 v100, v100
	v_lshlrev_b32_e32 v105, 16, v152
	v_exp_f32_e32 v103, v103
	v_and_b32_e32 v111, 0xffff0000, v152
	v_pk_mul_f32 v[104:105], v[100:101], v[104:105]
	v_mov_b64_e32 v[126:127], v[66:67]
	v_add_f32_e32 v100, v105, v108
	v_mul_f32_e32 v112, v104, v100
	v_lshlrev_b32_e32 v104, 16, v155
	v_add_f32_e32 v100, 1.0, v103
	v_mul_f32_e32 v103, 0xbfb8aa3b, v104
	v_rcp_f32_e32 v100, v100
	v_exp_f32_e32 v103, v103
	v_and_b32_e32 v108, 0xffff0000, v155
	v_mov_b64_e32 v[122:123], v[78:79]
	v_pk_mul_f32 v[110:111], v[100:101], v[110:111]
	v_add_f32_e32 v100, 1.0, v103
	v_mul_f32_e32 v103, 0xbfb8aa3b, v108
	v_rcp_f32_e32 v100, v100
	v_exp_f32_e32 v103, v103
	v_add_f32_e32 v105, v111, v109
	v_mul_f32_e32 v110, v110, v105
	v_lshlrev_b32_e32 v105, 16, v153
	v_pk_mul_f32 v[104:105], v[100:101], v[104:105]
	v_add_f32_e32 v100, 1.0, v103
	v_rcp_f32_e32 v100, v100
	v_add_f32_e32 v103, v105, v106
	v_and_b32_e32 v109, 0xffff0000, v153
	v_mul_f32_e32 v103, v104, v103
	v_pk_mul_f32 v[104:105], v[100:101], v[108:109]
	v_pk_mul_f32 v[108:109], v[102:103], v[116:117] op_sel_hi:[0,1]
	v_add_f32_e32 v100, v105, v107
	v_mul_f32_e32 v100, v104, v100
	v_cvt_pk_bf16_f32 v104, v112, v110
	v_cvt_pk_bf16_f32 v105, v103, v100
	v_mov_b32_e32 v210, v104
	v_mov_b32_e32 v211, v105
	v_add_u32_e32 v225, v224, v182
	s_nop 0
	v_permlane16_swap_b32_e32 v208, v210
	v_permlane16_swap_b32_e32 v209, v211
	global_store_dwordx4 v225, v[208:211], s[18:19]
	s_waitcnt vmcnt(6)
; __device__ __forceinline__ unsigned cvt_pk_bf16(float lo, float hi) { unsigned r; asm volatile("v_cvt_pk_bf16_f32 %0, %1, %2" : "=v"(r) : "v"(lo), "v"(hi)); return r; }
; __device__ __forceinline__ float silu_f(float x) { return x * __builtin_amdgcn_rcpf(1.0f + __builtin_amdgcn_exp2f(-x * LOG2E)); }
;     ...
;         for (int db = 0; db < 8; ++db) { f32x4 v = o[db] * wb;
;             const size_t ocol = (size_t)h * 128 + 16 * db + 4 * fq;
;             if (PASS > 0) { v[0] += wa * bf_lo(pv[db].x); v[1] += wa * bf_hi(pv[db].x); v[2] += wa * bf_lo(pv[db].y); v[3] += wa * bf_hi(pv[db].y); }
;             if (PASS < 2) { u32x2 ov; ov.x = pg8::cvt_pk_bf16(v[0], v[1]); ov.y = pg8::cvt_pk_bf16(v[2], v[3]); *(u32x2*)((char*)OACC + ((unsigned)(h * MT + qrow) * 256u + (unsigned)(32 * db + 8 * fq))) = ov; }
;             else { v[0] *= pg8::silu_f(bf_lo(gv[db].x)); v[1] *= pg8::silu_f(bf_hi(gv[db].x)); v[2] *= pg8::silu_f(bf_lo(gv[db].y)); v[3] *= pg8::silu_f(bf_hi(gv[db].y));
;                 u32x2 ov; ov.x = pg8::cvt_pk_bf16(v[0], v[1]); ov.y = pg8::cvt_pk_bf16(v[2], v[3]); *(u32x2*)((char*)RB + ((unsigned)qrow * (unsigned)(LDB * 2) + (unsigned)(h * 256 + 32 * db + 8 * fq))) = ov; } }
	v_lshlrev_b32_e32 v104, 16, v150
	v_mul_f32_e32 v100, 0xbfb8aa3b, v104
	v_exp_f32_e32 v100, v100
	v_and_b32_e32 v110, 0xffff0000, v150
	v_pk_mul_f32 v[106:107], v[102:103], v[118:119] op_sel_hi:[0,1]
	v_mul_f32_e32 v103, 0xbfb8aa3b, v110
	v_add_f32_e32 v100, 1.0, v100
	v_rcp_f32_e32 v100, v100
	v_lshlrev_b32_e32 v105, 16, v148
	v_exp_f32_e32 v103, v103
	v_and_b32_e32 v111, 0xffff0000, v148
	v_pk_mul_f32 v[104:105], v[100:101], v[104:105]
	v_readlane_b32 s1, v255, 22
	v_add_f32_e32 v100, v105, v108
	v_mul_f32_e32 v112, v104, v100
	v_lshlrev_b32_e32 v104, 16, v151
	v_add_f32_e32 v100, 1.0, v103
	v_mul_f32_e32 v103, 0xbfb8aa3b, v104
	v_rcp_f32_e32 v100, v100
	v_exp_f32_e32 v103, v103
	v_and_b32_e32 v108, 0xffff0000, v151
	v_writelane_b32 v255, s35, 20
	v_pk_mul_f32 v[110:111], v[100:101], v[110:111]
	v_add_f32_e32 v100, 1.0, v103
	v_mul_f32_e32 v103, 0xbfb8aa3b, v108
	v_rcp_f32_e32 v100, v100
	v_exp_f32_e32 v103, v103
	v_add_f32_e32 v105, v111, v109
	v_mul_f32_e32 v110, v110, v105
	v_lshlrev_b32_e32 v105, 16, v149
	v_pk_mul_f32 v[104:105], v[100:101], v[104:105]
	v_add_f32_e32 v100, 1.0, v103
	v_rcp_f32_e32 v100, v100
	v_add_f32_e32 v103, v105, v106
	v_and_b32_e32 v109, 0xffff0000, v149
	v_mul_f32_e32 v103, v104, v103
	v_pk_mul_f32 v[104:105], v[100:101], v[108:109]
	s_waitcnt vmcnt(5)
	v_and_b32_e32 v106, 0xffff0000, v146
	v_add_f32_e32 v100, v105, v107
	v_mul_f32_e32 v100, v104, v100
	v_cvt_pk_bf16_f32 v104, v112, v110
	v_cvt_pk_bf16_f32 v105, v103, v100
	v_mov_b32_e32 v212, v104
	v_mov_b32_e32 v213, v105
	v_lshlrev_b32_e32 v104, 16, v146
	v_mul_f32_e32 v100, 0xbfb8aa3b, v104
	v_exp_f32_e32 v100, v100
	v_pk_mul_f32 v[98:99], v[102:103], v[98:99] op_sel_hi:[0,1]
	v_pk_mul_f32 v[96:97], v[102:103], v[96:97] op_sel_hi:[0,1]
	v_mul_f32_e32 v103, 0xbfb8aa3b, v106
	v_add_f32_e32 v100, 1.0, v100
	v_rcp_f32_e32 v100, v100
	v_exp_f32_e32 v103, v103
	v_lshlrev_b32_e32 v105, 16, v144
	v_and_b32_e32 v107, 0xffff0000, v144
	v_pk_mul_f32 v[104:105], v[100:101], v[104:105]
	s_andn2_b64 vcc, exec, s[16:17]
	v_add_f32_e32 v96, v105, v96
	v_mul_f32_e32 v108, v104, v96
	v_add_f32_e32 v96, 1.0, v103
	v_rcp_f32_e32 v100, v96
	v_lshlrev_b32_e32 v96, 16, v147
	v_mul_f32_e32 v103, 0xbfb8aa3b, v96
	v_exp_f32_e32 v103, v103
	v_pk_mul_f32 v[104:105], v[100:101], v[106:107]
	v_and_b32_e32 v106, 0xffff0000, v147
	v_add_f32_e32 v97, v105, v97
	v_add_f32_e32 v100, 1.0, v103
	v_mul_f32_e32 v103, 0xbfb8aa3b, v106
	v_rcp_f32_e32 v100, v100
	v_exp_f32_e32 v103, v103
	v_mul_f32_e32 v104, v104, v97
	v_lshlrev_b32_e32 v97, 16, v145
	v_pk_mul_f32 v[96:97], v[100:101], v[96:97]
	v_add_f32_e32 v100, 1.0, v103
	v_rcp_f32_e32 v100, v100
	v_add_f32_e32 v97, v97, v98
	v_and_b32_e32 v107, 0xffff0000, v145
	v_mul_f32_e32 v98, v96, v97
	v_pk_mul_f32 v[96:97], v[100:101], v[106:107]
	v_pk_mul_f32 v[92:93], v[102:103], v[92:93] op_sel_hi:[0,1]
	v_add_f32_e32 v97, v97, v99
	v_mul_f32_e32 v97, v96, v97
	v_cvt_pk_bf16_f32 v96, v108, v104
	v_cvt_pk_bf16_f32 v97, v98, v97
	v_mov_b32_e32 v214, v96
	v_mov_b32_e32 v215, v97
	v_add_u32_e32 v225, v224, v165
	s_nop 0
	v_permlane16_swap_b32_e32 v212, v214
	v_permlane16_swap_b32_e32 v213, v215
	global_store_dwordx4 v225, v[212:215], s[18:19]
	s_waitcnt vmcnt(5)
	v_lshlrev_b32_e32 v96, 16, v142
	v_mul_f32_e32 v97, 0xbfb8aa3b, v96
	v_exp_f32_e32 v98, v97
	v_lshlrev_b32_e32 v97, 16, v140
	v_pk_mul_f32 v[94:95], v[102:103], v[94:95] op_sel_hi:[0,1]
	v_mov_b64_e32 v[124:125], v[64:65]
	v_add_f32_e32 v98, 1.0, v98
	v_rcp_f32_e32 v100, v98
	v_and_b32_e32 v98, 0xffff0000, v142
	v_mul_f32_e32 v99, 0xbfb8aa3b, v98
	v_exp_f32_e32 v99, v99
	v_pk_mul_f32 v[96:97], v[100:101], v[96:97]
	v_mov_b64_e32 v[120:121], v[76:77]
	v_add_f32_e32 v92, v97, v92
	v_mul_f32_e32 v103, v96, v92
	v_add_f32_e32 v92, 1.0, v99
	v_rcp_f32_e32 v100, v92
	v_lshlrev_b32_e32 v92, 16, v143
	v_mul_f32_e32 v96, 0xbfb8aa3b, v92
	v_exp_f32_e32 v104, v96
	v_and_b32_e32 v99, 0xffff0000, v140
	v_pk_mul_f32 v[96:97], v[100:101], v[98:99]
	v_and_b32_e32 v98, 0xffff0000, v143
	v_add_f32_e32 v93, v97, v93
	v_add_f32_e32 v97, 1.0, v104
	v_rcp_f32_e32 v100, v97
	v_mul_f32_e32 v97, 0xbfb8aa3b, v98
	v_exp_f32_e32 v97, v97
	v_mul_f32_e32 v96, v96, v93
	v_lshlrev_b32_e32 v93, 16, v141
	v_pk_mul_f32 v[92:93], v[100:101], v[92:93]
	v_add_f32_e32 v97, 1.0, v97
	v_rcp_f32_e32 v100, v97
	v_add_f32_e32 v93, v93, v94
	v_and_b32_e32 v99, 0xffff0000, v141
	v_mul_f32_e32 v94, v92, v93
	v_pk_mul_f32 v[92:93], v[100:101], v[98:99]
	v_pk_mul_f32 v[88:89], v[102:103], v[88:89] op_sel_hi:[0,1]
	v_add_f32_e32 v93, v93, v95
	v_mul_f32_e32 v93, v92, v93
	v_cvt_pk_bf16_f32 v92, v103, v96
	v_cvt_pk_bf16_f32 v93, v94, v93
	v_mov_b32_e32 v216, v92
	v_mov_b32_e32 v217, v93
	s_waitcnt vmcnt(4)
; __device__ __forceinline__ unsigned cvt_pk_bf16(float lo, float hi) { unsigned r; asm volatile("v_cvt_pk_bf16_f32 %0, %1, %2" : "=v"(r) : "v"(lo), "v"(hi)); return r; }
; __device__ __forceinline__ float silu_f(float x) { return x * __builtin_amdgcn_rcpf(1.0f + __builtin_amdgcn_exp2f(-x * LOG2E)); }
;     ...
;         for (int db = 0; db < 8; ++db) { f32x4 v = o[db] * wb;
;             const size_t ocol = (size_t)h * 128 + 16 * db + 4 * fq;
;             if (PASS > 0) { v[0] += wa * bf_lo(pv[db].x); v[1] += wa * bf_hi(pv[db].x); v[2] += wa * bf_lo(pv[db].y); v[3] += wa * bf_hi(pv[db].y); }
;             if (PASS < 2) { u32x2 ov; ov.x = pg8::cvt_pk_bf16(v[0], v[1]); ov.y = pg8::cvt_pk_bf16(v[2], v[3]); *(u32x2*)((char*)OACC + ((unsigned)(h * MT + qrow) * 256u + (unsigned)(32 * db + 8 * fq))) = ov; }
;             else { v[0] *= pg8::silu_f(bf_lo(gv[db].x)); v[1] *= pg8::silu_f(bf_hi(gv[db].x)); v[2] *= pg8::silu_f(bf_lo(gv[db].y)); v[3] *= pg8::silu_f(bf_hi(gv[db].y));
;                 u32x2 ov; ov.x = pg8::cvt_pk_bf16(v[0], v[1]); ov.y = pg8::cvt_pk_bf16(v[2], v[3]); *(u32x2*)((char*)RB + ((unsigned)qrow * (unsigned)(LDB * 2) + (unsigned)(h * 256 + 32 * db + 8 * fq))) = ov; } }
;         asm volatile("s_waitcnt lgkmcnt(0)\n\ts_barrier" ::: "memory");
	v_lshlrev_b32_e32 v92, 16, v138
	v_mul_f32_e32 v93, 0xbfb8aa3b, v92
	v_exp_f32_e32 v94, v93
	v_lshlrev_b32_e32 v93, 16, v136
	v_pk_mul_f32 v[90:91], v[102:103], v[90:91] op_sel_hi:[0,1]
	v_pk_mul_f32 v[84:85], v[102:103], v[84:85] op_sel_hi:[0,1]
	v_add_f32_e32 v94, 1.0, v94
	v_rcp_f32_e32 v100, v94
	v_and_b32_e32 v94, 0xffff0000, v138
	v_mul_f32_e32 v95, 0xbfb8aa3b, v94
	v_exp_f32_e32 v95, v95
	v_pk_mul_f32 v[92:93], v[100:101], v[92:93]
	v_pk_mul_f32 v[86:87], v[102:103], v[86:87] op_sel_hi:[0,1]
	v_add_f32_e32 v88, v93, v88
	v_mul_f32_e32 v96, v92, v88
	v_add_f32_e32 v88, 1.0, v95
	v_rcp_f32_e32 v100, v88
	v_lshlrev_b32_e32 v88, 16, v139
	v_mul_f32_e32 v92, 0xbfb8aa3b, v88
	v_exp_f32_e32 v97, v92
	v_and_b32_e32 v95, 0xffff0000, v136
	v_pk_mul_f32 v[92:93], v[100:101], v[94:95]
	v_and_b32_e32 v94, 0xffff0000, v139
	v_add_f32_e32 v89, v93, v89
	v_add_f32_e32 v93, 1.0, v97
	v_rcp_f32_e32 v100, v93
	v_mul_f32_e32 v93, 0xbfb8aa3b, v94
	v_exp_f32_e32 v93, v93
	v_mul_f32_e32 v92, v92, v89
	v_lshlrev_b32_e32 v89, 16, v137
	v_pk_mul_f32 v[88:89], v[100:101], v[88:89]
	v_add_f32_e32 v93, 1.0, v93
	v_rcp_f32_e32 v100, v93
	v_add_f32_e32 v89, v89, v90
	v_and_b32_e32 v95, 0xffff0000, v137
	v_mul_f32_e32 v90, v88, v89
	v_pk_mul_f32 v[88:89], v[100:101], v[94:95]
	v_pk_mul_f32 v[80:81], v[102:103], v[80:81] op_sel_hi:[0,1]
	v_add_f32_e32 v89, v89, v91
	v_mul_f32_e32 v89, v88, v89
	v_cvt_pk_bf16_f32 v88, v96, v92
	v_cvt_pk_bf16_f32 v89, v90, v89
	v_mov_b32_e32 v218, v88
	v_mov_b32_e32 v219, v89
	v_add_u32_e32 v225, v224, v163
	s_nop 0
	v_permlane16_swap_b32_e32 v216, v218
	v_permlane16_swap_b32_e32 v217, v219
	global_store_dwordx4 v225, v[216:219], s[18:19]
	s_waitcnt vmcnt(4)
	v_lshlrev_b32_e32 v88, 16, v134
	v_mul_f32_e32 v89, 0xbfb8aa3b, v88
	v_exp_f32_e32 v90, v89
	v_lshlrev_b32_e32 v89, 16, v132
	v_pk_mul_f32 v[82:83], v[102:103], v[82:83] op_sel_hi:[0,1]
	s_mov_b32 s2, s30
	v_add_f32_e32 v90, 1.0, v90
	v_rcp_f32_e32 v100, v90
	v_and_b32_e32 v90, 0xffff0000, v134
	v_mul_f32_e32 v91, 0xbfb8aa3b, v90
	v_exp_f32_e32 v91, v91
	v_pk_mul_f32 v[88:89], v[100:101], v[88:89]
	s_nop 0
	v_add_f32_e32 v84, v89, v84
	v_mul_f32_e32 v92, v88, v84
	v_add_f32_e32 v84, 1.0, v91
	v_rcp_f32_e32 v100, v84
	v_lshlrev_b32_e32 v84, 16, v135
	v_mul_f32_e32 v88, 0xbfb8aa3b, v84
	v_exp_f32_e32 v93, v88
	v_and_b32_e32 v91, 0xffff0000, v132
	v_pk_mul_f32 v[88:89], v[100:101], v[90:91]
	v_and_b32_e32 v90, 0xffff0000, v135
	v_add_f32_e32 v85, v89, v85
	v_add_f32_e32 v89, 1.0, v93
	v_rcp_f32_e32 v100, v89
	v_mul_f32_e32 v89, 0xbfb8aa3b, v90
	v_exp_f32_e32 v89, v89
	v_mul_f32_e32 v88, v88, v85
	v_lshlrev_b32_e32 v85, 16, v133
	v_pk_mul_f32 v[84:85], v[100:101], v[84:85]
	v_add_f32_e32 v89, 1.0, v89
	v_rcp_f32_e32 v100, v89
	v_add_f32_e32 v85, v85, v86
	v_and_b32_e32 v91, 0xffff0000, v133
	v_mul_f32_e32 v86, v84, v85
	v_pk_mul_f32 v[84:85], v[100:101], v[90:91]
	v_mov_b64_e32 v[134:135], v[74:75]
	v_add_f32_e32 v85, v85, v87
	v_mul_f32_e32 v85, v84, v85
	v_cvt_pk_bf16_f32 v84, v92, v88
	v_cvt_pk_bf16_f32 v85, v86, v85
	v_mov_b32_e32 v220, v84
	v_mov_b32_e32 v221, v85
	s_waitcnt vmcnt(3)
	v_lshlrev_b32_e32 v84, 16, v130
	v_mul_f32_e32 v85, 0xbfb8aa3b, v84
	v_exp_f32_e32 v86, v85
	v_lshlrev_b32_e32 v85, 16, v128
	v_mov_b64_e32 v[132:133], v[72:73]
	v_add_f32_e32 v86, 1.0, v86
	v_rcp_f32_e32 v100, v86
	v_and_b32_e32 v86, 0xffff0000, v130
	v_mul_f32_e32 v87, 0xbfb8aa3b, v86
	v_exp_f32_e32 v87, v87
	v_pk_mul_f32 v[84:85], v[100:101], v[84:85]
	s_nop 0
	v_add_f32_e32 v80, v85, v80
	v_mul_f32_e32 v88, v84, v80
	v_add_f32_e32 v80, 1.0, v87
	v_rcp_f32_e32 v100, v80
	v_lshlrev_b32_e32 v80, 16, v131
	v_mul_f32_e32 v84, 0xbfb8aa3b, v80
	v_exp_f32_e32 v89, v84
	v_and_b32_e32 v87, 0xffff0000, v128
	v_pk_mul_f32 v[84:85], v[100:101], v[86:87]
	v_and_b32_e32 v86, 0xffff0000, v131
	v_add_f32_e32 v81, v85, v81
	v_add_f32_e32 v85, 1.0, v89
	v_rcp_f32_e32 v100, v85
	v_mul_f32_e32 v85, 0xbfb8aa3b, v86
	v_exp_f32_e32 v85, v85
	v_mul_f32_e32 v84, v84, v81
	v_lshlrev_b32_e32 v81, 16, v129
	v_pk_mul_f32 v[80:81], v[100:101], v[80:81]
	v_add_f32_e32 v85, 1.0, v85
	v_rcp_f32_e32 v100, v85
	v_add_f32_e32 v81, v81, v82
	v_and_b32_e32 v87, 0xffff0000, v129
	v_mul_f32_e32 v82, v80, v81
	v_pk_mul_f32 v[80:81], v[100:101], v[86:87]
	v_mov_b64_e32 v[130:131], v[70:71]
	v_add_f32_e32 v81, v81, v83
	v_mul_f32_e32 v81, v80, v81
	v_cvt_pk_bf16_f32 v80, v88, v84
	v_cvt_pk_bf16_f32 v81, v82, v81
	v_mov_b32_e32 v222, v80
	v_mov_b32_e32 v223, v81
	v_add_u32_e32 v225, v224, v161
	s_nop 0
	v_permlane16_swap_b32_e32 v220, v222
	v_permlane16_swap_b32_e32 v221, v223
	global_store_dwordx4 v225, v[220:223], s[18:19]
	s_waitcnt lgkmcnt(0)
	s_barrier
	v_mov_b64_e32 v[128:129], v[68:69]
	s_cbranch_vccz .LBB0_631
